# DSA tile loop: K fragment reads issued up front with counted lgkmcnt, rolling V transpose-reads
# baseline (speedup 1.0000x reference)
; #define MFMA(a, b, c) __builtin_amdgcn_mfma_f32_32x32x16_bf16((a), (b), (c), 0, 0, 0)
; DI int crow(int reg, int hi) { return (reg & 3) + 8 * (reg >> 2) + 4 * hi; }
; template <int KSTR, int ND, int N>
; DI f32x16 s_block(unsigned kaddr, const bf16x8* qf, const f32x16& z16) {
;   bf16x8 f[4];
;   rd4<N * 32 * KSTR>(f, kaddr);
;   f32x16 a = MFMA(f[0], qf[0], z16); a = MFMA(f[1], qf[1], a); a = MFMA(f[2], qf[2], a); a = MFMA(f[3], qf[3], a);
;   if constexpr (ND > 4) { rd4<N * 32 * KSTR + 128>(f, kaddr); a = MFMA(f[0], qf[4], a); a = MFMA(f[1], qf[5], a); a = MFMA(f[2], qf[6], a); a = MFMA(f[3], qf[7], a); }
; template <int DQK, int W1, int DV, int VW, int MODE> ...
;     ...
;         const bool far = (tq0 - (kb + 63)) >= 128;
; #pragma unroll
;         for (int n = 0; n < 2; ++n) {
;           const unsigned wb = (n ? mw1 : mw0) >> (4 * hi);
;           if (far) {
; #pragma unroll
;             for (int i = 0; i < 16; ++i) {
;               const float v = fmaf(s[n][i], c2, bias_far);
;               s[n][i] = ((wb >> ((i & 3) + 8 * (i >> 2))) & 1u) ? v : NEGV;
;             }
;           } else {
; #pragma unroll
;             for (int i = 0; i < 16; ++i) {
;               const int key = kb + 32 * n + crow(i, hi);
;               int rel = tq - key; rel = rel < 0 ? 0 : (rel > 128 ? 128 : rel);
;               const float v = fmaf(s[n][i], c2, lutw[rel]);
;               s[n][i] = ((wb >> ((i & 3) + 8 * (i >> 2))) & 1u) ? v : NEGV;
;             }
;           }
.LBB0_1334:
	s_mov_b32 s54, s100
	v_add_u32_e32 v0, s54, v83
	ds_read_b128 v[34:37], v0
	ds_read_b128 v[38:41], v0 offset:32
	ds_read_b128 v[42:45], v0 offset:64
	ds_read_b128 v[46:49], v0 offset:96
	ds_read_b128 v[212:215], v0 offset:4608
	ds_read_b128 v[102:105], v0 offset:4640
	ds_read_b128 v[106:109], v0 offset:4672
	ds_read_b128 v[110:113], v0 offset:4704
	v_lshrrev_b32_e32 v121, v82, v116
	s_cmpk_lt_i32 s86, 0x80
	s_cselect_b64 s[18:19], -1, 0
	s_cmpk_gt_i32 s86, 0x7f
	s_mov_b64 s[0:1], -1
	s_waitcnt lgkmcnt(7)
	v_mfma_f32_32x32x16_bf16 v[50:65], v[34:37], v[66:69], 0
	v_add_u32_e32 v0, s86, v118
	s_waitcnt lgkmcnt(6)
	v_mfma_f32_32x32x16_bf16 v[50:65], v[38:41], v[70:73], v[50:65]
	v_and_b32_e32 v122, 0x4000000, v121
	v_and_b32_e32 v135, 2, v121
	v_and_b32_e32 v136, 1, v121
	v_and_b32_e32 v133, 8, v121
	v_and_b32_e32 v134, 4, v121
	v_and_b32_e32 v130, 0x200, v121
	v_and_b32_e32 v132, 0x100, v121
	s_waitcnt lgkmcnt(5)
	v_mfma_f32_32x32x16_bf16 v[50:65], v[42:45], v[74:77], v[50:65]
	v_and_b32_e32 v128, 0x800, v121
	v_and_b32_e32 v131, 0x400, v121
	v_and_b32_e32 v127, 0x20000, v121
	v_and_b32_e32 v129, 0x10000, v121
	v_and_b32_e32 v125, 0x80000, v121
	v_and_b32_e32 v126, 0x40000, v121
	v_and_b32_e32 v123, 0x2000000, v121
	v_and_b32_e32 v124, 0x1000000, v121
	s_waitcnt lgkmcnt(4)
	v_mfma_f32_32x32x16_bf16 v[50:65], v[46:49], v[78:81], v[50:65]
	v_cmp_ne_u32_e32 vcc, 0, v122
	s_waitcnt lgkmcnt(3)
	v_mfma_f32_32x32x16_bf16 v[34:49], v[212:215], v[66:69], 0
	s_waitcnt lgkmcnt(2)
	v_mfma_f32_32x32x16_bf16 v[34:49], v[102:105], v[70:73], v[34:49]
	s_waitcnt lgkmcnt(1)
	v_mfma_f32_32x32x16_bf16 v[34:49], v[106:109], v[74:77], v[34:49]
	s_waitcnt lgkmcnt(0)
	v_mfma_f32_32x32x16_bf16 v[34:49], v[110:113], v[78:81], v[34:49]
	s_cbranch_scc1 .LBB0_1336
	v_add_u32_e32 v102, 0xfffff85f, v0
	v_add_u32_e32 v103, 0xfffff85e, v0
	v_med3_i32 v102, v102, 0, v233
	v_med3_i32 v103, v103, 0, v233
	v_lshl_add_u32 v102, v102, 2, s27
	v_lshl_add_u32 v103, v103, 2, s27
	v_add_u32_e32 v104, 0xfffff85d, v0
	v_add_u32_e32 v105, 0xfffff85c, v0
	ds_read_b32 v102, v102
	ds_read_b32 v103, v103
	v_med3_i32 v104, v104, 0, v233
	v_med3_i32 v105, v105, 0, v233
	v_lshl_add_u32 v104, v104, 2, s27
	v_lshl_add_u32 v105, v105, 2, s27
	v_add_u32_e32 v106, 0xfffff857, v0
	v_add_u32_e32 v107, 0xfffff856, v0
	ds_read_b32 v104, v104
	ds_read_b32 v105, v105
	v_med3_i32 v106, v106, 0, v233
	v_med3_i32 v107, v107, 0, v233
	v_add_u32_e32 v108, 0xfffff855, v0
	v_add_u32_e32 v109, 0xfffff854, v0
	v_lshl_add_u32 v106, v106, 2, s27
	v_lshl_add_u32 v107, v107, 2, s27
	v_med3_i32 v108, v108, 0, v233
	v_med3_i32 v109, v109, 0, v233
	ds_read_b32 v106, v106
	ds_read_b32 v107, v107
	v_lshl_add_u32 v108, v108, 2, s27
	v_lshl_add_u32 v109, v109, 2, s27
	v_cmp_ne_u32_e64 s[0:1], 0, v136
	ds_read_b32 v108, v108
	ds_read_b32 v109, v109
	s_waitcnt lgkmcnt(0)
	v_pk_fma_f32 v[102:103], v[50:51], s[64:65], v[102:103] op_sel_hi:[1,0,1]
	v_add_u32_e32 v110, 0xfffff84f, v0
	v_add_u32_e32 v111, 0xfffff84e, v0
	v_cndmask_b32_e64 v102, v232, v102, s[0:1]
	v_cmp_ne_u32_e64 s[0:1], 0, v135
	v_med3_i32 v110, v110, 0, v233
	v_med3_i32 v111, v111, 0, v233
	v_cndmask_b32_e64 v103, v232, v103, s[0:1]
	v_pk_fma_f32 v[104:105], v[52:53], s[64:65], v[104:105] op_sel_hi:[1,0,1]
	v_cmp_ne_u32_e64 s[0:1], 0, v134
	v_lshl_add_u32 v110, v110, 2, s27
	v_lshl_add_u32 v111, v111, 2, s27
	v_add_u32_e32 v112, 0xfffff84d, v0
	v_add_u32_e32 v113, 0xfffff84c, v0
	v_cndmask_b32_e64 v104, v232, v104, s[0:1]
	v_cmp_ne_u32_e64 s[0:1], 0, v133
	ds_read_b32 v110, v110
	ds_read_b32 v111, v111
	v_med3_i32 v112, v112, 0, v233
	v_med3_i32 v113, v113, 0, v233
	v_cndmask_b32_e64 v105, v232, v105, s[0:1]
	v_pk_fma_f32 v[106:107], v[54:55], s[64:65], v[106:107] op_sel_hi:[1,0,1]
	v_cmp_ne_u32_e64 s[0:1], 0, v132
	v_lshl_add_u32 v112, v112, 2, s27
	v_lshl_add_u32 v113, v113, 2, s27
	v_add_u32_e32 v114, 0xfffff847, v0
	v_add_u32_e32 v115, 0xfffff846, v0
	v_cndmask_b32_e64 v106, v232, v106, s[0:1]
	v_cmp_ne_u32_e64 s[0:1], 0, v130
	ds_read_b32 v112, v112
	ds_read_b32 v113, v113
	v_med3_i32 v114, v114, 0, v233
	v_med3_i32 v115, v115, 0, v233
	v_add_u32_e32 v116, 0xfffff845, v0
	v_add_u32_e32 v120, 0xfffff844, v0
	v_cndmask_b32_e64 v107, v232, v107, s[0:1]
	v_pk_fma_f32 v[108:109], v[56:57], s[64:65], v[108:109] op_sel_hi:[1,0,1]
	v_cmp_ne_u32_e64 s[0:1], 0, v131
	v_lshl_add_u32 v114, v114, 2, s27
	v_lshl_add_u32 v115, v115, 2, s27
	v_med3_i32 v116, v116, 0, v233
	v_med3_i32 v120, v120, 0, v233
	v_cndmask_b32_e64 v108, v232, v108, s[0:1]
	v_cmp_ne_u32_e64 s[0:1], 0, v128
	ds_read_b32 v114, v114
	ds_read_b32 v115, v115
	v_lshl_add_u32 v116, v116, 2, s27
	v_lshl_add_u32 v120, v120, 2, s27
	v_cndmask_b32_e64 v109, v232, v109, s[0:1]
	v_cmp_ne_u32_e64 s[0:1], 0, v129
	ds_read_b32 v116, v116
	ds_read_b32 v120, v120
	s_waitcnt lgkmcnt(0)
	v_pk_fma_f32 v[110:111], v[58:59], s[64:65], v[110:111] op_sel_hi:[1,0,1]
	v_pk_fma_f32 v[112:113], v[60:61], s[64:65], v[112:113] op_sel_hi:[1,0,1]
	v_cndmask_b32_e64 v110, v232, v110, s[0:1]
	v_cmp_ne_u32_e64 s[0:1], 0, v127
	v_pk_fma_f32 v[114:115], v[62:63], s[64:65], v[114:115] op_sel_hi:[1,0,1]
	v_fmac_f32_e32 v116, 0x3e38aa3b, v64
	v_cndmask_b32_e64 v111, v232, v111, s[0:1]
	v_cmp_ne_u32_e64 s[0:1], 0, v126
	v_cndmask_b32_e32 v116, v232, v116, vcc
	v_fmac_f32_e32 v120, 0x3e38aa3b, v65
	v_cndmask_b32_e64 v112, v232, v112, s[0:1]
	v_cmp_ne_u32_e64 s[0:1], 0, v125
	s_nop 1
	v_cndmask_b32_e64 v113, v232, v113, s[0:1]
	v_cmp_ne_u32_e64 s[0:1], 0, v124
	s_nop 1
	v_cndmask_b32_e64 v114, v232, v114, s[0:1]
	v_cmp_ne_u32_e64 s[0:1], 0, v123
	s_nop 1
	v_cndmask_b32_e64 v115, v232, v115, s[0:1]
	s_mov_b64 s[0:1], 0

; #define MFMA(a, b, c) __builtin_amdgcn_mfma_f32_32x32x16_bf16((a), (b), (c), 0, 0, 0)
; template <int CB> DI void pv_block(f32x16& o, unsigned vaddr, const bf16x8 (&pb)[2][2]) {
;   s16x4 v[8];
;   rdv8<CB * 4096>(v, vaddr);
; #pragma unroll
;   for (int q = 0; q < 4; ++q) {
;     const bf16x8 vf = {v[2 * q][0], v[2 * q][1], v[2 * q][2], v[2 * q][3], v[2 * q + 1][0], v[2 * q + 1][1], v[2 * q + 1][2], v[2 * q + 1][3]};
;     o = MFMA(vf, pb[q >> 1][q & 1], o);
;   }
; }
; template <int DQK, int W1, int DV, int VW, int MODE> ...
;     ...
;         f32x16 e0 = s[0], e1 = s[1];
;         if (MODE != 0) { const float nm = -m; e0 = e0 + nm; e1 = e1 + nm; }
; #pragma unroll
;         for (int i = 0; i < 16; ++i) { e0[i] = __builtin_amdgcn_exp2f(e0[i]); e1[i] = __builtin_amdgcn_exp2f(e1[i]); }
;         s[0] = e0; s[1] = e1;
;         const f32x16 sm = e0 + e1;
;         typedef __attribute__((ext_vector_type(8))) float f32x8;
;         const f32x8 h8 = sm.lo + sm.hi;
;         const f32x4 h4 = h8.lo + h8.hi;
;         const f32x2 h2 = h4.lo + h4.hi;
;         l += h2[0] + h2[1];
;       }
;       bf16x8 pb[2][2];
; #pragma unroll
;       for (int n = 0; n < 2; ++n)
; #pragma unroll
;         for (int s2 = 0; s2 < 2; ++s2) {
;           u32x4 pw = {pk2(s[n][8 * s2 + 0], s[n][8 * s2 + 1]), pk2(s[n][8 * s2 + 2], s[n][8 * s2 + 3]),
;                       pk2(s[n][8 * s2 + 4], s[n][8 * s2 + 5]), pk2(s[n][8 * s2 + 6], s[n][8 * s2 + 7])};
;           pb[n][s2] = __builtin_bit_cast(bf16x8, pw);
;         }
;       pv_block<0>(o[0], bufa + vlane, pb);
;       if constexpr (NCB > 1) pv_block<1>(o[1], bufa + vlane, pb);
;       if constexpr (NCB > 2) pv_block<2>(o[2], bufa + vlane, pb);
;       if constexpr (NCB > 3) pv_block<3>(o[3], bufa + vlane, pb);
.LBB0_1344:
	v_pk_add_f32 v[34:35], v[116:117], v[98:99] op_sel_hi:[1,0] neg_lo:[0,1] neg_hi:[0,1]
	v_pk_add_f32 v[36:37], v[114:115], v[98:99] op_sel_hi:[1,0] neg_lo:[0,1] neg_hi:[0,1]
	v_pk_add_f32 v[38:39], v[112:113], v[98:99] op_sel_hi:[1,0] neg_lo:[0,1] neg_hi:[0,1]
	v_pk_add_f32 v[40:41], v[110:111], v[98:99] op_sel_hi:[1,0] neg_lo:[0,1] neg_hi:[0,1]
	v_pk_add_f32 v[42:43], v[108:109], v[98:99] op_sel_hi:[1,0] neg_lo:[0,1] neg_hi:[0,1]
	v_pk_add_f32 v[44:45], v[106:107], v[98:99] op_sel_hi:[1,0] neg_lo:[0,1] neg_hi:[0,1]
	v_pk_add_f32 v[46:47], v[104:105], v[98:99] op_sel_hi:[1,0] neg_lo:[0,1] neg_hi:[0,1]
	v_pk_add_f32 v[48:49], v[102:103], v[98:99] op_sel_hi:[1,0] neg_lo:[0,1] neg_hi:[0,1]
	v_pk_add_f32 v[64:65], v[64:65], v[98:99] op_sel_hi:[1,0] neg_lo:[0,1] neg_hi:[0,1]
	v_pk_add_f32 v[62:63], v[62:63], v[98:99] op_sel_hi:[1,0] neg_lo:[0,1] neg_hi:[0,1]
	v_pk_add_f32 v[60:61], v[60:61], v[98:99] op_sel_hi:[1,0] neg_lo:[0,1] neg_hi:[0,1]
	v_pk_add_f32 v[58:59], v[58:59], v[98:99] op_sel_hi:[1,0] neg_lo:[0,1] neg_hi:[0,1]
	v_pk_add_f32 v[56:57], v[56:57], v[98:99] op_sel_hi:[1,0] neg_lo:[0,1] neg_hi:[0,1]
	v_pk_add_f32 v[54:55], v[54:55], v[98:99] op_sel_hi:[1,0] neg_lo:[0,1] neg_hi:[0,1]
	v_pk_add_f32 v[52:53], v[52:53], v[98:99] op_sel_hi:[1,0] neg_lo:[0,1] neg_hi:[0,1]
	v_pk_add_f32 v[50:51], v[50:51], v[98:99] op_sel_hi:[1,0] neg_lo:[0,1] neg_hi:[0,1]
	v_exp_f32_e32 v48, v48
	v_exp_f32_e32 v50, v50
	v_exp_f32_e32 v49, v49
	v_exp_f32_e32 v51, v51
	v_exp_f32_e32 v46, v46
	v_exp_f32_e32 v52, v52
	v_exp_f32_e32 v47, v47
	v_exp_f32_e32 v53, v53
	v_exp_f32_e32 v44, v44
	v_exp_f32_e32 v54, v54
	v_exp_f32_e32 v45, v45
	v_exp_f32_e32 v55, v55
	v_exp_f32_e32 v42, v42
	v_exp_f32_e32 v56, v56
	v_exp_f32_e32 v43, v43
	v_exp_f32_e32 v57, v57
	v_exp_f32_e32 v102, v40
	v_exp_f32_e32 v58, v58
	v_exp_f32_e32 v103, v41
	v_exp_f32_e32 v59, v59
	v_exp_f32_e32 v104, v38
	v_exp_f32_e32 v60, v60
	v_exp_f32_e32 v105, v39
	v_exp_f32_e32 v61, v61
	v_exp_f32_e32 v36, v36
	v_exp_f32_e32 v62, v62
	v_exp_f32_e32 v37, v37
	v_exp_f32_e32 v63, v63
	v_exp_f32_e32 v34, v34
	v_exp_f32_e32 v64, v64
	v_exp_f32_e32 v35, v35
	v_exp_f32_e32 v65, v65
	v_pk_add_f32 v[38:39], v[102:103], v[58:59]
	v_pk_add_f32 v[40:41], v[104:105], v[60:61]
	v_pk_add_f32 v[106:107], v[46:47], v[52:53]
	v_pk_add_f32 v[108:109], v[34:35], v[64:65]
	v_pk_add_f32 v[110:111], v[42:43], v[56:57]
	v_pk_add_f32 v[112:113], v[36:37], v[62:63]
	v_pk_add_f32 v[114:115], v[44:45], v[54:55]
	v_pk_add_f32 v[116:117], v[48:49], v[50:51]
	v_pk_add_f32 v[112:113], v[114:115], v[112:113]
	v_pk_add_f32 v[108:109], v[110:111], v[108:109]
	v_pk_add_f32 v[40:41], v[106:107], v[40:41]
	v_pk_add_f32 v[38:39], v[116:117], v[38:39]
	v_pk_add_f32 v[40:41], v[40:41], v[108:109]
	v_pk_add_f32 v[38:39], v[38:39], v[112:113]
	s_sub_i32 s86, s86, 64
	v_pk_add_f32 v[38:39], v[38:39], v[40:41]
	v_cvt_pk_bf16_f32 v40, v44, v45
	v_add_f32_e32 v0, v38, v39
	v_cvt_pk_bf16_f32 v38, v48, v49
	v_cvt_pk_bf16_f32 v39, v46, v47
	v_cvt_pk_bf16_f32 v41, v42, v43
	v_cvt_pk_bf16_f32 v44, v36, v37
	v_cvt_pk_bf16_f32 v45, v34, v35
	v_cvt_pk_bf16_f32 v46, v50, v51
	v_cvt_pk_bf16_f32 v47, v52, v53
	v_cvt_pk_bf16_f32 v48, v54, v55
	v_cvt_pk_bf16_f32 v49, v56, v57
	v_cvt_pk_bf16_f32 v34, v58, v59
	v_cvt_pk_bf16_f32 v35, v60, v61
	v_cvt_pk_bf16_f32 v36, v62, v63
	v_cvt_pk_bf16_f32 v37, v64, v65
	v_add_f32_e32 v119, v119, v0
	v_add_u32_e32 v0, s54, v99
	ds_read_b64_tr_b16 v[62:63], v0
	ds_read_b64_tr_b16 v[64:65], v0 offset:512
	ds_read_b64_tr_b16 v[58:59], v0 offset:1024
	ds_read_b64_tr_b16 v[60:61], v0 offset:1536
	ds_read_b64_tr_b16 v[54:55], v0 offset:2048
	ds_read_b64_tr_b16 v[56:57], v0 offset:2560
	ds_read_b64_tr_b16 v[50:51], v0 offset:3072
	ds_read_b64_tr_b16 v[52:53], v0 offset:3584
	v_cvt_pk_bf16_f32 v42, v102, v103
	v_cvt_pk_bf16_f32 v43, v104, v105
	s_add_i32 s94, s94, 64
	s_waitcnt lgkmcnt(6)
	v_mfma_f32_32x32x16_bf16 v[18:33], v[62:65], v[38:41], v[18:33]
	ds_read_b64_tr_b16 v[62:63], v0 offset:4096
	ds_read_b64_tr_b16 v[64:65], v0 offset:4608
	s_waitcnt lgkmcnt(6)
	v_mfma_f32_32x32x16_bf16 v[18:33], v[58:61], v[42:45], v[18:33]
	ds_read_b64_tr_b16 v[58:59], v0 offset:5120
	ds_read_b64_tr_b16 v[60:61], v0 offset:5632
	s_waitcnt lgkmcnt(6)
	v_mfma_f32_32x32x16_bf16 v[18:33], v[54:57], v[46:49], v[18:33]
	ds_read_b64_tr_b16 v[54:55], v0 offset:6144
	ds_read_b64_tr_b16 v[56:57], v0 offset:6656
	s_waitcnt lgkmcnt(6)
	v_mfma_f32_32x32x16_bf16 v[18:33], v[50:53], v[34:37], v[18:33]
	ds_read_b64_tr_b16 v[50:51], v0 offset:7168
	ds_read_b64_tr_b16 v[52:53], v0 offset:7680
	s_cmp_ge_u32 s95, s69
	s_cbranch_scc1 .Ldsa_w0
	s_waitcnt vmcnt(2)
	s_branch .Ldsa_wd
